# prompt-DSA softmax: wave all-reduces via DPP and permlane swaps instead of ds_bpermute round trips
# baseline (speedup 1.0000x reference)
.LBB0_1331:
	s_and_b32 s8, s8, -16
	v_readlane_b32 s2, v250, 34
	v_cmp_gt_i32_e64 s[0:1], s8, v207
	s_waitcnt vmcnt(0)
	v_mov_b32_e32 v2, 0xff800000
	v_lshl_add_u32 v0, v207, 4, s2
	v_mov_b32_e32 v6, 0xff800000
	v_mov_b32_e32 v7, 0xff800000
	v_mov_b32_e32 v8, 0xff800000
	v_mov_b32_e32 v9, 0xff800000
	s_and_saveexec_b64 s[2:3], s[0:1]
	ds_read_b128 v[6:9], v0
	s_or_b64 exec, exec, s[2:3]
	v_readlane_b32 s4, v250, 34
	v_cmp_gt_i32_e64 s[2:3], s8, v84
	v_mov_b32_e32 v3, 0xff800000
	v_lshl_add_u32 v26, v84, 4, s4
	v_mov_b32_e32 v4, 0xff800000
	v_mov_b32_e32 v5, 0xff800000
	s_and_saveexec_b64 s[4:5], s[2:3]
	ds_read_b128 v[2:5], v26
	s_or_b64 exec, exec, s[4:5]
	v_readlane_b32 s6, v250, 34
	v_cmp_gt_i32_e64 s[4:5], s8, v83
	v_mov_b32_e32 v10, 0xff800000
	v_lshl_add_u32 v27, v83, 4, s6
	v_mov_b32_e32 v14, 0xff800000
	v_mov_b32_e32 v15, 0xff800000
	v_mov_b32_e32 v16, 0xff800000
	v_mov_b32_e32 v17, 0xff800000
	s_and_saveexec_b64 s[6:7], s[4:5]
	ds_read_b128 v[14:17], v27
	s_or_b64 exec, exec, s[6:7]
	v_cmp_gt_i32_e64 s[6:7], s8, v82
	v_readlane_b32 s8, v250, 34
	v_mov_b32_e32 v11, 0xff800000
	v_mov_b32_e32 v12, 0xff800000
	v_lshl_add_u32 v28, v82, 4, s8
	v_mov_b32_e32 v13, 0xff800000
	s_and_saveexec_b64 s[8:9], s[6:7]
	ds_read_b128 v[10:13], v28
	s_or_b64 exec, exec, s[8:9]
	v_cmp_lt_i32_e32 vcc, v181, v180
	s_mov_b32 s8, 0xff800000
	s_waitcnt lgkmcnt(0)
	v_max3_f32 v18, v6, s8, v2
	v_cndmask_b32_e32 v22, v178, v181, vcc
	v_cmp_lt_i32_e32 vcc, v173, v180
	v_lshlrev_b32_e32 v31, 2, v22
	v_max3_f32 v18, v18, v14, v10
	v_cndmask_b32_e32 v22, v178, v173, vcc
	v_cmp_lt_i32_e32 vcc, v230, v180
	v_lshlrev_b32_e32 v30, 2, v22
	v_max3_f32 v19, v7, s8, v3
	v_cndmask_b32_e32 v22, v178, v230, vcc
	v_cmp_lt_i32_e32 vcc, v248, v180
	v_lshlrev_b32_e32 v29, 2, v22
	v_max3_f32 v19, v19, v15, v11
	v_cndmask_b32_e32 v22, v178, v248, vcc
	v_cmp_lt_i32_e32 vcc, v186, v180
	v_lshlrev_b32_e32 v209, 2, v22
	v_max3_f32 v20, v8, s8, v4
	v_cndmask_b32_e32 v22, v178, v186, vcc
	v_lshlrev_b32_e32 v208, 2, v22
	v_max3_f32 v20, v20, v16, v12
	v_max3_f32 v21, v9, s8, v5
	v_max3_f32 v21, v21, v17, v13
	s_nop 1
	v_max_f32_dpp v18, v18, v18 quad_perm:[1,0,3,2] row_mask:0xf bank_mask:0xf
	v_max_f32_dpp v19, v19, v19 quad_perm:[1,0,3,2] row_mask:0xf bank_mask:0xf
	v_max_f32_dpp v20, v20, v20 quad_perm:[1,0,3,2] row_mask:0xf bank_mask:0xf
	v_max_f32_dpp v21, v21, v21 quad_perm:[1,0,3,2] row_mask:0xf bank_mask:0xf
	v_max_f32_dpp v18, v18, v18 quad_perm:[2,3,0,1] row_mask:0xf bank_mask:0xf
	v_max_f32_dpp v19, v19, v19 quad_perm:[2,3,0,1] row_mask:0xf bank_mask:0xf
	v_max_f32_dpp v20, v20, v20 quad_perm:[2,3,0,1] row_mask:0xf bank_mask:0xf
	v_max_f32_dpp v21, v21, v21 quad_perm:[2,3,0,1] row_mask:0xf bank_mask:0xf
	v_max_f32_dpp v18, v18, v18 row_half_mirror row_mask:0xf bank_mask:0xf
	v_max_f32_dpp v19, v19, v19 row_half_mirror row_mask:0xf bank_mask:0xf
	v_max_f32_dpp v20, v20, v20 row_half_mirror row_mask:0xf bank_mask:0xf
	v_max_f32_dpp v21, v21, v21 row_half_mirror row_mask:0xf bank_mask:0xf
	v_max_f32_dpp v18, v18, v18 row_mirror row_mask:0xf bank_mask:0xf
	v_max_f32_dpp v19, v19, v19 row_mirror row_mask:0xf bank_mask:0xf
	v_max_f32_dpp v20, v20, v20 row_mirror row_mask:0xf bank_mask:0xf
	v_max_f32_dpp v21, v21, v21 row_mirror row_mask:0xf bank_mask:0xf
	s_nop 1
	v_mov_b32_e32 v22, v18
	v_mov_b32_e32 v23, v19
	v_mov_b32_e32 v24, v20
	v_mov_b32_e32 v25, v21
	s_nop 1
	v_permlane16_swap_b32 v22, v18
	v_permlane16_swap_b32 v23, v19
	v_permlane16_swap_b32 v24, v20
	v_permlane16_swap_b32 v25, v21
	s_nop 1
	v_max_f32_e32 v18, v18, v22
	v_max_f32_e32 v19, v19, v23
	v_max_f32_e32 v20, v20, v24
	v_max_f32_e32 v21, v21, v25
	s_nop 1
	v_mov_b32_e32 v22, v18
	v_mov_b32_e32 v23, v19
	v_mov_b32_e32 v24, v20
	v_mov_b32_e32 v25, v21
	s_nop 1
	v_permlane32_swap_b32 v22, v18
	v_permlane32_swap_b32 v23, v19
	v_permlane32_swap_b32 v24, v20
	v_permlane32_swap_b32 v25, v21
	s_nop 1
	v_max_f32_e32 v32, v18, v22
	v_max_f32_e32 v33, v19, v23
	v_max_f32_e32 v34, v20, v24
	v_max_f32_e32 v35, v21, v25
	v_sub_f32_e32 v2, v2, v32
	v_mul_f32_e32 v2, 0x3fb8aa3b, v2
	v_sub_f32_e32 v6, v6, v32
	v_mul_f32_e32 v6, 0x3fb8aa3b, v6
	v_exp_f32_e32 v22, v6
	v_sub_f32_e32 v6, v7, v33
	v_mul_f32_e32 v6, 0x3fb8aa3b, v6
	v_exp_f32_e32 v23, v6
	v_sub_f32_e32 v6, v8, v34
	v_mul_f32_e32 v6, 0x3fb8aa3b, v6
	v_exp_f32_e32 v24, v6
	v_exp_f32_e32 v18, v2
	v_sub_f32_e32 v2, v3, v33
	v_mul_f32_e32 v2, 0x3fb8aa3b, v2
	v_exp_f32_e32 v19, v2
	v_sub_f32_e32 v2, v4, v34
	v_mul_f32_e32 v2, 0x3fb8aa3b, v2
	v_exp_f32_e32 v20, v2
	v_sub_f32_e32 v2, v5, v35
	v_mul_f32_e32 v2, 0x3fb8aa3b, v2
	v_sub_f32_e32 v6, v9, v35
	v_exp_f32_e32 v21, v2
	v_sub_f32_e32 v2, v14, v32
	v_mul_f32_e32 v6, 0x3fb8aa3b, v6
	v_mul_f32_e32 v2, 0x3fb8aa3b, v2
	v_exp_f32_e32 v25, v6
	v_exp_f32_e32 v6, v2
	v_sub_f32_e32 v2, v15, v33
	v_mul_f32_e32 v2, 0x3fb8aa3b, v2
	v_exp_f32_e32 v7, v2
	v_sub_f32_e32 v2, v16, v34
	v_mul_f32_e32 v2, 0x3fb8aa3b, v2
	v_exp_f32_e32 v8, v2
	v_sub_f32_e32 v2, v17, v35
	v_mul_f32_e32 v2, 0x3fb8aa3b, v2
	v_exp_f32_e32 v9, v2
	v_sub_f32_e32 v2, v10, v32
	v_sub_f32_e32 v3, v11, v33
	v_sub_f32_e32 v4, v12, v34
	v_sub_f32_e32 v5, v13, v35
	v_mul_f32_e32 v2, 0x3fb8aa3b, v2
	v_mul_f32_e32 v3, 0x3fb8aa3b, v3
	v_mul_f32_e32 v4, 0x3fb8aa3b, v4
	v_mul_f32_e32 v5, 0x3fb8aa3b, v5
	v_exp_f32_e32 v2, v2
	v_exp_f32_e32 v3, v3
	v_exp_f32_e32 v4, v4
	v_exp_f32_e32 v5, v5
	v_pk_add_f32 v[10:11], v[22:23], 0 op_sel_hi:[1,0]
	v_pk_add_f32 v[14:15], v[24:25], 0 op_sel_hi:[1,0]
	v_pk_add_f32 v[10:11], v[18:19], v[10:11]
	v_pk_add_f32 v[14:15], v[20:21], v[14:15]
	v_pk_add_f32 v[10:11], v[6:7], v[10:11]
	v_pk_add_f32 v[14:15], v[8:9], v[14:15]
	v_pk_add_f32 v[10:11], v[2:3], v[10:11]
	v_pk_add_f32 v[14:15], v[4:5], v[14:15]
	s_nop 1
	v_add_f32_dpp v10, v10, v10 quad_perm:[1,0,3,2] row_mask:0xf bank_mask:0xf
	v_add_f32_dpp v11, v11, v11 quad_perm:[1,0,3,2] row_mask:0xf bank_mask:0xf
	v_add_f32_dpp v14, v14, v14 quad_perm:[1,0,3,2] row_mask:0xf bank_mask:0xf
	v_add_f32_dpp v15, v15, v15 quad_perm:[1,0,3,2] row_mask:0xf bank_mask:0xf
	v_add_f32_dpp v10, v10, v10 quad_perm:[2,3,0,1] row_mask:0xf bank_mask:0xf
	v_add_f32_dpp v11, v11, v11 quad_perm:[2,3,0,1] row_mask:0xf bank_mask:0xf
	v_add_f32_dpp v14, v14, v14 quad_perm:[2,3,0,1] row_mask:0xf bank_mask:0xf
	v_add_f32_dpp v15, v15, v15 quad_perm:[2,3,0,1] row_mask:0xf bank_mask:0xf
	v_add_f32_dpp v10, v10, v10 row_half_mirror row_mask:0xf bank_mask:0xf
	v_add_f32_dpp v11, v11, v11 row_half_mirror row_mask:0xf bank_mask:0xf
	v_add_f32_dpp v14, v14, v14 row_half_mirror row_mask:0xf bank_mask:0xf
	v_add_f32_dpp v15, v15, v15 row_half_mirror row_mask:0xf bank_mask:0xf
	v_add_f32_dpp v10, v10, v10 row_mirror row_mask:0xf bank_mask:0xf
	v_add_f32_dpp v11, v11, v11 row_mirror row_mask:0xf bank_mask:0xf
	v_add_f32_dpp v14, v14, v14 row_mirror row_mask:0xf bank_mask:0xf
	v_add_f32_dpp v15, v15, v15 row_mirror row_mask:0xf bank_mask:0xf
	s_nop 1
	v_mov_b32_e32 v12, v10
	v_mov_b32_e32 v13, v11
	v_mov_b32_e32 v16, v14
	v_mov_b32_e32 v17, v15
	s_nop 1
	v_permlane16_swap_b32 v12, v10
	v_permlane16_swap_b32 v13, v11
	v_permlane16_swap_b32 v16, v14
	v_permlane16_swap_b32 v17, v15
	s_nop 1
	v_add_f32_e32 v10, v10, v12
	v_add_f32_e32 v11, v11, v13
	v_add_f32_e32 v14, v14, v16
	v_add_f32_e32 v15, v15, v17
	s_nop 1
	v_mov_b32_e32 v12, v10
	v_mov_b32_e32 v13, v11
	v_mov_b32_e32 v16, v14
	v_mov_b32_e32 v17, v15
	s_nop 1
	v_permlane32_swap_b32 v12, v10
	v_permlane32_swap_b32 v13, v11
	v_permlane32_swap_b32 v16, v14
	v_permlane32_swap_b32 v17, v15
	s_nop 1
	v_add_f32_e32 v10, v10, v12
	v_add_f32_e32 v11, v11, v13
	v_add_f32_e32 v14, v14, v16
	v_add_f32_e32 v15, v15, v17
	v_mov_b32_e32 v12, v10
	v_mov_b32_e32 v13, v11
	v_mov_b32_e32 v10, v14
	v_mov_b32_e32 v11, v15
	s_nop 0
	v_div_scale_f32 v14, s[8:9], v11, v11, 1.0
	v_rcp_f32_e32 v15, v14
	s_nop 0
	v_fma_f32 v16, -v14, v15, 1.0
	v_fmac_f32_e32 v15, v16, v15
	v_div_scale_f32 v16, vcc, 1.0, v11, 1.0
	v_mul_f32_e32 v17, v16, v15
	v_fma_f32 v32, -v14, v17, v16
	v_fmac_f32_e32 v17, v32, v15
	v_fma_f32 v14, -v14, v17, v16
	v_div_fmas_f32 v14, v14, v15, v17
	v_div_fixup_f32 v11, v14, v11, 1.0
	v_div_scale_f32 v14, s[8:9], v10, v10, 1.0
	v_rcp_f32_e32 v15, v14
	s_nop 0
	v_fma_f32 v16, -v14, v15, 1.0
	v_fmac_f32_e32 v15, v16, v15
	v_div_scale_f32 v16, vcc, 1.0, v10, 1.0
	v_mul_f32_e32 v17, v16, v15
	v_fma_f32 v32, -v14, v17, v16
	v_fmac_f32_e32 v17, v32, v15
	v_fma_f32 v14, -v14, v17, v16
	v_div_fmas_f32 v14, v14, v15, v17
	v_div_fixup_f32 v10, v14, v10, 1.0
	v_div_scale_f32 v14, s[8:9], v13, v13, 1.0
	v_rcp_f32_e32 v15, v14
	s_nop 0
	v_fma_f32 v16, -v14, v15, 1.0
	v_fmac_f32_e32 v15, v16, v15
	v_div_scale_f32 v16, vcc, 1.0, v13, 1.0
	v_mul_f32_e32 v17, v16, v15
	v_fma_f32 v32, -v14, v17, v16
	v_fmac_f32_e32 v17, v32, v15
	v_fma_f32 v14, -v14, v17, v16
	v_div_fmas_f32 v14, v14, v15, v17
	v_div_fixup_f32 v13, v14, v13, 1.0
	v_div_scale_f32 v14, s[8:9], v12, v12, 1.0
	v_rcp_f32_e32 v15, v14
	s_nop 0
	v_fma_f32 v16, -v14, v15, 1.0
	v_fmac_f32_e32 v15, v16, v15
	v_div_scale_f32 v16, vcc, 1.0, v12, 1.0
	v_mul_f32_e32 v17, v16, v15
	v_fma_f32 v32, -v14, v17, v16
	v_fmac_f32_e32 v17, v32, v15
	v_fma_f32 v14, -v14, v17, v16
	v_div_fmas_f32 v14, v14, v15, v17
	v_div_fixup_f32 v12, v14, v12, 1.0
	s_and_saveexec_b64 s[8:9], s[0:1]
	s_cbranch_execz .LBB0_1343
	v_pk_mul_f32 v[16:17], v[24:25], v[10:11]
	v_pk_mul_f32 v[14:15], v[22:23], v[12:13]
	ds_write_b128 v0, v[14:17]
	s_or_b64 exec, exec, s[8:9]
	s_and_saveexec_b64 s[8:9], s[2:3]
	s_cbranch_execnz .LBB0_1344

.LBB0_1347:
	s_or_b64 exec, exec, s[8:9]
	v_mov_b32_e32 v2, 0xff800000
	v_mov_b32_e32 v6, 0xff800000
	v_mov_b32_e32 v7, 0xff800000
	v_mov_b32_e32 v8, 0xff800000
	v_mov_b32_e32 v9, 0xff800000
	s_and_saveexec_b64 s[8:9], s[0:1]
	ds_read_b128 v[6:9], v0 offset:4096
	s_or_b64 exec, exec, s[8:9]
	v_mov_b32_e32 v3, 0xff800000
	v_mov_b32_e32 v4, 0xff800000
	v_mov_b32_e32 v5, 0xff800000
	s_and_saveexec_b64 s[8:9], s[2:3]
	ds_read_b128 v[2:5], v26 offset:4096
	s_or_b64 exec, exec, s[8:9]
	v_mov_b32_e32 v10, 0xff800000
	v_mov_b32_e32 v14, 0xff800000
	v_mov_b32_e32 v15, 0xff800000
	v_mov_b32_e32 v16, 0xff800000
	v_mov_b32_e32 v17, 0xff800000
	s_and_saveexec_b64 s[8:9], s[4:5]
	ds_read_b128 v[14:17], v27 offset:4096
	s_or_b64 exec, exec, s[8:9]
	v_mov_b32_e32 v11, 0xff800000
	v_mov_b32_e32 v12, 0xff800000
	v_mov_b32_e32 v13, 0xff800000
	s_and_saveexec_b64 s[8:9], s[6:7]
	ds_read_b128 v[10:13], v28 offset:4096
	s_or_b64 exec, exec, s[8:9]
	s_mov_b32 s8, 0xff800000
	s_waitcnt lgkmcnt(0)
	v_max3_f32 v18, v6, s8, v2
	v_max3_f32 v18, v18, v14, v10
	v_max3_f32 v19, v7, s8, v3
	v_max3_f32 v19, v19, v15, v11
	v_max3_f32 v20, v8, s8, v4
	v_max3_f32 v20, v20, v16, v12
	v_max3_f32 v21, v9, s8, v5
	v_max3_f32 v21, v21, v17, v13
	s_nop 1
	v_max_f32_dpp v18, v18, v18 quad_perm:[1,0,3,2] row_mask:0xf bank_mask:0xf
	v_max_f32_dpp v19, v19, v19 quad_perm:[1,0,3,2] row_mask:0xf bank_mask:0xf
	v_max_f32_dpp v20, v20, v20 quad_perm:[1,0,3,2] row_mask:0xf bank_mask:0xf
	v_max_f32_dpp v21, v21, v21 quad_perm:[1,0,3,2] row_mask:0xf bank_mask:0xf
	v_max_f32_dpp v18, v18, v18 quad_perm:[2,3,0,1] row_mask:0xf bank_mask:0xf
	v_max_f32_dpp v19, v19, v19 quad_perm:[2,3,0,1] row_mask:0xf bank_mask:0xf
	v_max_f32_dpp v20, v20, v20 quad_perm:[2,3,0,1] row_mask:0xf bank_mask:0xf
	v_max_f32_dpp v21, v21, v21 quad_perm:[2,3,0,1] row_mask:0xf bank_mask:0xf
	v_max_f32_dpp v18, v18, v18 row_half_mirror row_mask:0xf bank_mask:0xf
	v_max_f32_dpp v19, v19, v19 row_half_mirror row_mask:0xf bank_mask:0xf
	v_max_f32_dpp v20, v20, v20 row_half_mirror row_mask:0xf bank_mask:0xf
	v_max_f32_dpp v21, v21, v21 row_half_mirror row_mask:0xf bank_mask:0xf
	v_max_f32_dpp v18, v18, v18 row_mirror row_mask:0xf bank_mask:0xf
	v_max_f32_dpp v19, v19, v19 row_mirror row_mask:0xf bank_mask:0xf
	v_max_f32_dpp v20, v20, v20 row_mirror row_mask:0xf bank_mask:0xf
	v_max_f32_dpp v21, v21, v21 row_mirror row_mask:0xf bank_mask:0xf
	s_nop 1
	v_mov_b32_e32 v22, v18
	v_mov_b32_e32 v23, v19
	v_mov_b32_e32 v24, v20
	v_mov_b32_e32 v25, v21
	s_nop 1
	v_permlane16_swap_b32 v22, v18
	v_permlane16_swap_b32 v23, v19
	v_permlane16_swap_b32 v24, v20
	v_permlane16_swap_b32 v25, v21
	s_nop 1
	v_max_f32_e32 v18, v18, v22
	v_max_f32_e32 v19, v19, v23
	v_max_f32_e32 v20, v20, v24
	v_max_f32_e32 v21, v21, v25
	s_nop 1
	v_mov_b32_e32 v22, v18
	v_mov_b32_e32 v23, v19
	v_mov_b32_e32 v24, v20
	v_mov_b32_e32 v25, v21
	s_nop 1
	v_permlane32_swap_b32 v22, v18
	v_permlane32_swap_b32 v23, v19
	v_permlane32_swap_b32 v24, v20
	v_permlane32_swap_b32 v25, v21
	s_nop 1
	v_max_f32_e32 v32, v18, v22
	v_max_f32_e32 v33, v19, v23
	v_max_f32_e32 v34, v20, v24
	v_max_f32_e32 v35, v21, v25
	v_sub_f32_e32 v2, v2, v32
	v_mul_f32_e32 v2, 0x3fb8aa3b, v2
	v_sub_f32_e32 v6, v6, v32
	v_mul_f32_e32 v6, 0x3fb8aa3b, v6
	v_exp_f32_e32 v22, v6
	v_sub_f32_e32 v6, v7, v33
	v_mul_f32_e32 v6, 0x3fb8aa3b, v6
	v_exp_f32_e32 v23, v6
	v_sub_f32_e32 v6, v8, v34
	v_mul_f32_e32 v6, 0x3fb8aa3b, v6
	v_exp_f32_e32 v24, v6
	v_exp_f32_e32 v18, v2
	v_sub_f32_e32 v2, v3, v33
	v_mul_f32_e32 v2, 0x3fb8aa3b, v2
	v_exp_f32_e32 v19, v2
	v_sub_f32_e32 v2, v4, v34
	v_mul_f32_e32 v2, 0x3fb8aa3b, v2
	v_exp_f32_e32 v20, v2
	v_sub_f32_e32 v2, v5, v35
	v_mul_f32_e32 v2, 0x3fb8aa3b, v2
	v_sub_f32_e32 v6, v9, v35
	v_exp_f32_e32 v21, v2
	v_sub_f32_e32 v2, v14, v32
	v_mul_f32_e32 v6, 0x3fb8aa3b, v6
	v_mul_f32_e32 v2, 0x3fb8aa3b, v2
	v_exp_f32_e32 v25, v6
	v_exp_f32_e32 v6, v2
	v_sub_f32_e32 v2, v15, v33
	v_mul_f32_e32 v2, 0x3fb8aa3b, v2
	v_exp_f32_e32 v7, v2
	v_sub_f32_e32 v2, v16, v34
	v_mul_f32_e32 v2, 0x3fb8aa3b, v2
	v_exp_f32_e32 v8, v2
	v_sub_f32_e32 v2, v17, v35
	v_mul_f32_e32 v2, 0x3fb8aa3b, v2
	v_exp_f32_e32 v9, v2
	v_sub_f32_e32 v2, v10, v32
	v_sub_f32_e32 v3, v11, v33
	v_sub_f32_e32 v4, v12, v34
	v_sub_f32_e32 v5, v13, v35
	v_mul_f32_e32 v2, 0x3fb8aa3b, v2
	v_mul_f32_e32 v3, 0x3fb8aa3b, v3
	v_mul_f32_e32 v4, 0x3fb8aa3b, v4
	v_mul_f32_e32 v5, 0x3fb8aa3b, v5
	v_exp_f32_e32 v2, v2
	v_exp_f32_e32 v3, v3
	v_exp_f32_e32 v4, v4
	v_exp_f32_e32 v5, v5
	v_pk_add_f32 v[10:11], v[22:23], 0 op_sel_hi:[1,0]
	v_pk_add_f32 v[14:15], v[24:25], 0 op_sel_hi:[1,0]
	v_pk_add_f32 v[10:11], v[18:19], v[10:11]
	v_pk_add_f32 v[14:15], v[20:21], v[14:15]
	v_pk_add_f32 v[10:11], v[6:7], v[10:11]
	v_pk_add_f32 v[14:15], v[8:9], v[14:15]
	v_pk_add_f32 v[10:11], v[2:3], v[10:11]
	v_pk_add_f32 v[14:15], v[4:5], v[14:15]
	s_nop 1
	v_add_f32_dpp v10, v10, v10 quad_perm:[1,0,3,2] row_mask:0xf bank_mask:0xf
	v_add_f32_dpp v11, v11, v11 quad_perm:[1,0,3,2] row_mask:0xf bank_mask:0xf
	v_add_f32_dpp v14, v14, v14 quad_perm:[1,0,3,2] row_mask:0xf bank_mask:0xf
	v_add_f32_dpp v15, v15, v15 quad_perm:[1,0,3,2] row_mask:0xf bank_mask:0xf
	v_add_f32_dpp v10, v10, v10 quad_perm:[2,3,0,1] row_mask:0xf bank_mask:0xf
	v_add_f32_dpp v11, v11, v11 quad_perm:[2,3,0,1] row_mask:0xf bank_mask:0xf
	v_add_f32_dpp v14, v14, v14 quad_perm:[2,3,0,1] row_mask:0xf bank_mask:0xf
	v_add_f32_dpp v15, v15, v15 quad_perm:[2,3,0,1] row_mask:0xf bank_mask:0xf
	v_add_f32_dpp v10, v10, v10 row_half_mirror row_mask:0xf bank_mask:0xf
	v_add_f32_dpp v11, v11, v11 row_half_mirror row_mask:0xf bank_mask:0xf
	v_add_f32_dpp v14, v14, v14 row_half_mirror row_mask:0xf bank_mask:0xf
	v_add_f32_dpp v15, v15, v15 row_half_mirror row_mask:0xf bank_mask:0xf
	v_add_f32_dpp v10, v10, v10 row_mirror row_mask:0xf bank_mask:0xf
	v_add_f32_dpp v11, v11, v11 row_mirror row_mask:0xf bank_mask:0xf
	v_add_f32_dpp v14, v14, v14 row_mirror row_mask:0xf bank_mask:0xf
	v_add_f32_dpp v15, v15, v15 row_mirror row_mask:0xf bank_mask:0xf
	s_nop 1
	v_mov_b32_e32 v12, v10
	v_mov_b32_e32 v13, v11
	v_mov_b32_e32 v16, v14
	v_mov_b32_e32 v17, v15
	s_nop 1
	v_permlane16_swap_b32 v12, v10
	v_permlane16_swap_b32 v13, v11
	v_permlane16_swap_b32 v16, v14
	v_permlane16_swap_b32 v17, v15
	s_nop 1
	v_add_f32_e32 v10, v10, v12
	v_add_f32_e32 v11, v11, v13
	v_add_f32_e32 v14, v14, v16
	v_add_f32_e32 v15, v15, v17
	s_nop 1
	v_mov_b32_e32 v12, v10
	v_mov_b32_e32 v13, v11
	v_mov_b32_e32 v16, v14
	v_mov_b32_e32 v17, v15
	s_nop 1
	v_permlane32_swap_b32 v12, v10
	v_permlane32_swap_b32 v13, v11
	v_permlane32_swap_b32 v16, v14
	v_permlane32_swap_b32 v17, v15
	s_nop 1
	v_add_f32_e32 v10, v10, v12
	v_add_f32_e32 v11, v11, v13
	v_add_f32_e32 v14, v14, v16
	v_add_f32_e32 v15, v15, v17
	v_mov_b32_e32 v12, v10
	v_mov_b32_e32 v13, v11
	v_mov_b32_e32 v10, v14
	v_mov_b32_e32 v11, v15
	s_nop 0
	v_div_scale_f32 v14, s[8:9], v11, v11, 1.0
	v_rcp_f32_e32 v15, v14
	s_nop 0
	v_fma_f32 v16, -v14, v15, 1.0
	v_fmac_f32_e32 v15, v16, v15
	v_div_scale_f32 v16, vcc, 1.0, v11, 1.0
	v_mul_f32_e32 v17, v16, v15
	v_fma_f32 v29, -v14, v17, v16
	v_fmac_f32_e32 v17, v29, v15
	v_fma_f32 v14, -v14, v17, v16
	v_div_fmas_f32 v14, v14, v15, v17
	v_div_fixup_f32 v11, v14, v11, 1.0
	v_div_scale_f32 v14, s[8:9], v10, v10, 1.0
	v_rcp_f32_e32 v15, v14
	s_nop 0
	v_fma_f32 v16, -v14, v15, 1.0
	v_fmac_f32_e32 v15, v16, v15
	v_div_scale_f32 v16, vcc, 1.0, v10, 1.0
	v_mul_f32_e32 v17, v16, v15
	v_fma_f32 v29, -v14, v17, v16
	v_fmac_f32_e32 v17, v29, v15
	v_fma_f32 v14, -v14, v17, v16
	v_div_fmas_f32 v14, v14, v15, v17
	v_div_fixup_f32 v10, v14, v10, 1.0
	v_div_scale_f32 v14, s[8:9], v13, v13, 1.0
	v_rcp_f32_e32 v15, v14
	s_nop 0
	v_fma_f32 v16, -v14, v15, 1.0
	v_fmac_f32_e32 v15, v16, v15
	v_div_scale_f32 v16, vcc, 1.0, v13, 1.0
	v_mul_f32_e32 v17, v16, v15
	v_fma_f32 v29, -v14, v17, v16
	v_fmac_f32_e32 v17, v29, v15
	v_fma_f32 v14, -v14, v17, v16
	v_div_fmas_f32 v14, v14, v15, v17
	v_div_fixup_f32 v13, v14, v13, 1.0
	v_div_scale_f32 v14, s[8:9], v12, v12, 1.0
	v_rcp_f32_e32 v15, v14
	s_nop 0
	v_fma_f32 v16, -v14, v15, 1.0
	v_fmac_f32_e32 v15, v16, v15
	v_div_scale_f32 v16, vcc, 1.0, v12, 1.0
	v_mul_f32_e32 v17, v16, v15
	v_fma_f32 v29, -v14, v17, v16
	v_fmac_f32_e32 v17, v29, v15
	v_fma_f32 v14, -v14, v17, v16
	v_div_fmas_f32 v14, v14, v15, v17
	v_div_fixup_f32 v12, v14, v12, 1.0
	s_and_saveexec_b64 s[8:9], s[0:1]
	s_cbranch_execz .LBB0_1359
	v_pk_mul_f32 v[16:17], v[24:25], v[10:11]
	v_pk_mul_f32 v[14:15], v[22:23], v[12:13]
	ds_write_b128 v0, v[14:17] offset:4096
	s_or_b64 exec, exec, s[8:9]
	s_and_saveexec_b64 s[0:1], s[2:3]
	s_cbranch_execnz .LBB0_1360
